# attention softmax with packed-f32 subtract and packed row-sum accumulation
# baseline (speedup 1.0000x reference)
.LBB0_533:
	v_sub_f32_e32 v16, v187, v186
	v_pk_add_f32 v[98:99], v[98:99], v[16:17] op_sel_hi:[1,0] neg_lo:[0,1] neg_hi:[0,1]
	v_pk_add_f32 v[100:101], v[100:101], v[16:17] op_sel_hi:[1,0] neg_lo:[0,1] neg_hi:[0,1]
	v_pk_add_f32 v[102:103], v[102:103], v[16:17] op_sel_hi:[1,0] neg_lo:[0,1] neg_hi:[0,1]
	v_pk_add_f32 v[104:105], v[104:105], v[16:17] op_sel_hi:[1,0] neg_lo:[0,1] neg_hi:[0,1]
	v_pk_add_f32 v[106:107], v[106:107], v[16:17] op_sel_hi:[1,0] neg_lo:[0,1] neg_hi:[0,1]
	v_pk_add_f32 v[108:109], v[108:109], v[16:17] op_sel_hi:[1,0] neg_lo:[0,1] neg_hi:[0,1]
	v_pk_add_f32 v[110:111], v[110:111], v[16:17] op_sel_hi:[1,0] neg_lo:[0,1] neg_hi:[0,1]
	v_pk_add_f32 v[112:113], v[112:113], v[16:17] op_sel_hi:[1,0] neg_lo:[0,1] neg_hi:[0,1]
	v_pk_add_f32 v[82:83], v[82:83], v[16:17] op_sel_hi:[1,0] neg_lo:[0,1] neg_hi:[0,1]
	v_pk_add_f32 v[84:85], v[84:85], v[16:17] op_sel_hi:[1,0] neg_lo:[0,1] neg_hi:[0,1]
	v_pk_add_f32 v[86:87], v[86:87], v[16:17] op_sel_hi:[1,0] neg_lo:[0,1] neg_hi:[0,1]
	v_pk_add_f32 v[88:89], v[88:89], v[16:17] op_sel_hi:[1,0] neg_lo:[0,1] neg_hi:[0,1]
	v_pk_add_f32 v[90:91], v[90:91], v[16:17] op_sel_hi:[1,0] neg_lo:[0,1] neg_hi:[0,1]
	v_pk_add_f32 v[92:93], v[92:93], v[16:17] op_sel_hi:[1,0] neg_lo:[0,1] neg_hi:[0,1]
	v_pk_add_f32 v[94:95], v[94:95], v[16:17] op_sel_hi:[1,0] neg_lo:[0,1] neg_hi:[0,1]
	v_pk_add_f32 v[96:97], v[96:97], v[16:17] op_sel_hi:[1,0] neg_lo:[0,1] neg_hi:[0,1]
	v_exp_f32_e32 v186, v98
	v_exp_f32_e32 v188, v99
	v_exp_f32_e32 v226, v82
	v_exp_f32_e32 v189, v100
	v_exp_f32_e32 v227, v83
	v_exp_f32_e32 v213, v101
	v_exp_f32_e32 v228, v84
	v_exp_f32_e32 v214, v102
	v_exp_f32_e32 v229, v85
	v_exp_f32_e32 v215, v103
	v_exp_f32_e32 v230, v86
	v_exp_f32_e32 v216, v104
	v_exp_f32_e32 v231, v87
	v_exp_f32_e32 v217, v105
	v_exp_f32_e32 v232, v88
	v_exp_f32_e32 v218, v106
	v_exp_f32_e32 v233, v89
	v_exp_f32_e32 v219, v107
	v_exp_f32_e32 v234, v90
	v_exp_f32_e32 v220, v108
	v_exp_f32_e32 v235, v91
	v_exp_f32_e32 v221, v109
	v_exp_f32_e32 v236, v92
	v_exp_f32_e32 v222, v110
	v_exp_f32_e32 v237, v93
	v_exp_f32_e32 v223, v111
	v_exp_f32_e32 v238, v94
	v_exp_f32_e32 v224, v112
	v_exp_f32_e32 v239, v95
	v_exp_f32_e32 v225, v113
	v_exp_f32_e32 v240, v96
	v_exp_f32_e32 v241, v97
	s_mov_b64 s[74:75], -1
	s_and_b64 vcc, exec, s[12:13]
	v_cvt_pk_bf16_f32 v94, v186, v188
	v_cvt_pk_bf16_f32 v95, v189, v213
	v_cvt_pk_bf16_f32 v96, v214, v215
	v_cvt_pk_bf16_f32 v97, v216, v217
	v_cvt_pk_bf16_f32 v90, v218, v219
	v_cvt_pk_bf16_f32 v91, v220, v221
	v_cvt_pk_bf16_f32 v92, v222, v223
	v_cvt_pk_bf16_f32 v93, v224, v225
	v_cvt_pk_bf16_f32 v86, v226, v227
	v_cvt_pk_bf16_f32 v87, v228, v229
	v_cvt_pk_bf16_f32 v88, v230, v231
	v_cvt_pk_bf16_f32 v89, v232, v233
	v_cvt_pk_bf16_f32 v82, v234, v235
	v_cvt_pk_bf16_f32 v83, v236, v237
	v_cvt_pk_bf16_f32 v84, v238, v239
	v_cvt_pk_bf16_f32 v85, v240, v241
	s_cbranch_vccz .LBB0_535
	s_waitcnt vmcnt(0)
	s_mov_b64 s[74:75], 0

.LBB0_543:
	v_pk_add_f32 v[4:5], v[188:189], v[214:215]
	v_pk_add_f32 v[4:5], v[4:5], v[216:217]
	v_pk_add_f32 v[4:5], v[4:5], v[218:219]
	v_pk_add_f32 v[4:5], v[4:5], v[220:221]
	v_pk_add_f32 v[4:5], v[4:5], v[222:223]
	v_pk_add_f32 v[4:5], v[4:5], v[224:225]
	v_pk_add_f32 v[4:5], v[4:5], v[226:227]
	v_pk_add_f32 v[4:5], v[4:5], v[228:229]
	v_pk_add_f32 v[4:5], v[4:5], v[230:231]
	v_pk_add_f32 v[4:5], v[4:5], v[232:233]
	v_pk_add_f32 v[4:5], v[4:5], v[234:235]
	v_pk_add_f32 v[4:5], v[4:5], v[236:237]
	v_pk_add_f32 v[4:5], v[4:5], v[238:239]
	v_pk_add_f32 v[4:5], v[4:5], v[240:241]
	v_add_f32_e32 v4, v4, v5
	v_add_f32_e32 v4, v186, v4
	v_add_f32_e32 v4, v213, v4
	v_add_f32_e32 v207, v207, v4
	v_sub_f32_e32 v4, v17, v16
	v_pk_add_f32 v[98:99], v[98:99], v[4:5] op_sel_hi:[1,0] neg_lo:[0,1] neg_hi:[0,1]
	v_pk_add_f32 v[100:101], v[100:101], v[4:5] op_sel_hi:[1,0] neg_lo:[0,1] neg_hi:[0,1]
	v_pk_add_f32 v[102:103], v[102:103], v[4:5] op_sel_hi:[1,0] neg_lo:[0,1] neg_hi:[0,1]
	v_pk_add_f32 v[104:105], v[104:105], v[4:5] op_sel_hi:[1,0] neg_lo:[0,1] neg_hi:[0,1]
	v_pk_add_f32 v[106:107], v[106:107], v[4:5] op_sel_hi:[1,0] neg_lo:[0,1] neg_hi:[0,1]
	v_pk_add_f32 v[108:109], v[108:109], v[4:5] op_sel_hi:[1,0] neg_lo:[0,1] neg_hi:[0,1]
	v_pk_add_f32 v[110:111], v[110:111], v[4:5] op_sel_hi:[1,0] neg_lo:[0,1] neg_hi:[0,1]
	v_pk_add_f32 v[112:113], v[112:113], v[4:5] op_sel_hi:[1,0] neg_lo:[0,1] neg_hi:[0,1]
	v_pk_add_f32 v[82:83], v[82:83], v[4:5] op_sel_hi:[1,0] neg_lo:[0,1] neg_hi:[0,1]
	v_pk_add_f32 v[84:85], v[84:85], v[4:5] op_sel_hi:[1,0] neg_lo:[0,1] neg_hi:[0,1]
	v_pk_add_f32 v[86:87], v[86:87], v[4:5] op_sel_hi:[1,0] neg_lo:[0,1] neg_hi:[0,1]
	v_pk_add_f32 v[88:89], v[88:89], v[4:5] op_sel_hi:[1,0] neg_lo:[0,1] neg_hi:[0,1]
	v_pk_add_f32 v[90:91], v[90:91], v[4:5] op_sel_hi:[1,0] neg_lo:[0,1] neg_hi:[0,1]
	v_pk_add_f32 v[92:93], v[92:93], v[4:5] op_sel_hi:[1,0] neg_lo:[0,1] neg_hi:[0,1]
	v_pk_add_f32 v[94:95], v[94:95], v[4:5] op_sel_hi:[1,0] neg_lo:[0,1] neg_hi:[0,1]
	v_pk_add_f32 v[96:97], v[96:97], v[4:5] op_sel_hi:[1,0] neg_lo:[0,1] neg_hi:[0,1]
	v_exp_f32_e32 v5, v98
	v_exp_f32_e32 v7, v99
	v_exp_f32_e32 v8, v100
	v_exp_f32_e32 v9, v101
	v_exp_f32_e32 v10, v102
	v_exp_f32_e32 v11, v103
	v_exp_f32_e32 v12, v104
	v_exp_f32_e32 v13, v105
	v_exp_f32_e32 v14, v106
	v_exp_f32_e32 v15, v107
	v_exp_f32_e32 v16, v108
	v_exp_f32_e32 v98, v109
	v_exp_f32_e32 v99, v110
	v_exp_f32_e32 v100, v111
	v_exp_f32_e32 v101, v112
	v_exp_f32_e32 v102, v113
	v_exp_f32_e32 v103, v82
	v_exp_f32_e32 v104, v83
	v_exp_f32_e32 v105, v84
	v_exp_f32_e32 v106, v85
	v_exp_f32_e32 v107, v86
	v_exp_f32_e32 v108, v87
	v_exp_f32_e32 v109, v88
	v_exp_f32_e32 v110, v89
	v_exp_f32_e32 v90, v90
	v_exp_f32_e32 v91, v91
	v_exp_f32_e32 v92, v92
	v_exp_f32_e32 v93, v93
	v_exp_f32_e32 v94, v94
	v_exp_f32_e32 v95, v95
	v_exp_f32_e32 v96, v96
	v_exp_f32_e32 v97, v97
	v_pk_add_f32 v[84:85], v[8:9], v[10:11]
	v_pk_add_f32 v[84:85], v[84:85], v[12:13]
	v_pk_add_f32 v[84:85], v[84:85], v[14:15]
	v_pk_add_f32 v[84:85], v[84:85], v[98:99]
	v_pk_add_f32 v[84:85], v[84:85], v[100:101]
	v_pk_add_f32 v[84:85], v[84:85], v[102:103]
	v_pk_add_f32 v[84:85], v[84:85], v[104:105]
	v_pk_add_f32 v[84:85], v[84:85], v[106:107]
	v_pk_add_f32 v[84:85], v[84:85], v[108:109]
	v_pk_add_f32 v[84:85], v[84:85], v[90:91]
	v_pk_add_f32 v[84:85], v[84:85], v[92:93]
	v_pk_add_f32 v[84:85], v[84:85], v[94:95]
	v_pk_add_f32 v[84:85], v[84:85], v[96:97]
	v_add_f32_e32 v4, v84, v85
	v_add_f32_e32 v4, v5, v4
	v_add_f32_e32 v4, v7, v4
	v_add_f32_e32 v4, v16, v4
	v_add_f32_e32 v4, v110, v4
	v_add_f32_e32 v2, v2, v4
	v_cvt_pk_bf16_f32 v4, v90, v91
	ds_read_b64_tr_b16 v[90:91], v200 offset:0
	v_cvt_pk_bf16_f32 v82, v5, v7
	v_cvt_pk_bf16_f32 v5, v92, v93
	ds_read_b64_tr_b16 v[92:93], v200 offset:1024
	v_cvt_pk_bf16_f32 v6, v94, v95
	ds_read_b64_tr_b16 v[94:95], v200 offset:2048
	v_cvt_pk_bf16_f32 v7, v96, v97
	ds_read_b64_tr_b16 v[96:97], v200 offset:3072
	v_cvt_pk_bf16_f32 v87, v16, v98
	v_cvt_pk_bf16_f32 v88, v99, v100
	ds_read_b64_tr_b16 v[98:99], v200 offset:4096
	v_cvt_pk_bf16_f32 v89, v101, v102
	ds_read_b64_tr_b16 v[100:101], v200 offset:5120
	v_cvt_pk_bf16_f32 v83, v8, v9
	v_cvt_pk_bf16_f32 v8, v103, v104
	ds_read_b64_tr_b16 v[102:103], v200 offset:6144
	v_cvt_pk_bf16_f32 v9, v105, v106
	ds_read_b64_tr_b16 v[104:105], v200 offset:7168
	v_cvt_pk_bf16_f32 v84, v10, v11
	v_cvt_pk_bf16_f32 v10, v107, v108
	ds_read_b64_tr_b16 v[106:107], v201 offset:0
	v_cvt_pk_bf16_f32 v11, v109, v110
	ds_read_b64_tr_b16 v[108:109], v201 offset:1024
	ds_read_b64_tr_b16 v[110:111], v201 offset:2048
	ds_read_b64_tr_b16 v[112:113], v201 offset:3072
	ds_read_b64_tr_b16 v[146:147], v201 offset:4096
	ds_read_b64_tr_b16 v[148:149], v201 offset:5120
	v_cvt_pk_bf16_f32 v85, v12, v13
	ds_read_b64_tr_b16 v[12:13], v201 offset:6144
	v_cvt_pk_bf16_f32 v86, v14, v15
	ds_read_b64_tr_b16 v[14:15], v201 offset:7168
	v_add_u32_e32 v208, 0xffffff00, v208
	s_waitcnt lgkmcnt(0)
	s_add_i32 s89, s89, 64
	v_mfma_f32_32x32x16_bf16 v[34:49], v[90:93], v[82:85], v[34:49]
	s_andn2_b64 vcc, exec, s[12:13]
	v_mfma_f32_32x32x16_bf16 v[18:33], v[106:109], v[82:85], v[18:33]
	v_mfma_f32_32x32x16_bf16 v[34:49], v[94:97], v[86:89], v[34:49]
	v_mfma_f32_32x32x16_bf16 v[18:33], v[110:113], v[86:89], v[18:33]
	v_mfma_f32_32x32x16_bf16 v[34:49], v[98:101], v[8:11], v[34:49]
	v_mfma_f32_32x32x16_bf16 v[18:33], v[146:149], v[8:11], v[18:33]
	v_mfma_f32_32x32x16_bf16 v[34:49], v[102:105], v[4:7], v[34:49]
	v_mfma_f32_32x32x16_bf16 v[18:33], v[12:15], v[4:7], v[18:33]
	s_cbranch_vccz .LBB0_545
	s_mov_b32 s33, s11
	s_branch .LBB0_525
